# RWKV lora GEMM epilogue rewritten: bias loaded once per tile, no per-8-column wait on the previous store
# speedup vs baseline: 1.0064x; 1.0064x over previous
;     __device__ __forceinline__ bool apply(f32x4 (&acc)[2][2][4][2], const pg8::Unit& u, int wr, int wc, int fr, int fq) const {
;         if (kind != K_BR3) { (*this)(acc, u, wr, wc, fr, fq); return false; }
.LBB0_462:
	s_cmp_eq_u32 s28, 3
	s_cbranch_scc1 .Llo_epi
	s_cmp_eq_u32 s28, 5
	s_cbranch_scc1 .Lwo_epi
	s_cmp_eq_u32 s28, 7
	s_cbranch_scc0 .Lfx_no
	v_readlane_b32 s98, v255, 12
	s_cmpk_gt_u32 s98, 24
	s_cbranch_scc1 .Lfn_epi

; __device__ __forceinline__ float sigmoidf_(float x) { return __builtin_amdgcn_rcpf(1.f + __expf(-x)); }
;     __device__ __forceinline__ void emit(int row, int pn, int col0, float* v) const {
;     ...
;         case K_LORA: {
;             if (col0 < 512) {
; #pragma unroll
;                 for (int j = 0; j < 8; ++j) v[j] = 0.6065306597126334f * sigmoidf_(v[j] + f0[col0 + j]); }
;             else if (col0 < 1024) {
; #pragma unroll
;                 for (int j = 0; j < 8; ++j) v[j] = sigmoidf_(v[j] + f1[col0 - 512 + j]); }
;             store8((bf16_t*)(ws + WS_WAG) + (size_t)row * 1536 + col0, v);
;         } break;
;     __device__ __forceinline__ void operator()(const f32x4 (&acc)[2][2][4][2], const pg8::Unit& u, int wr, int wc, int fr, int fq) const {
;         const int row0 = u.pm * 256 + wr * 64 + fr, colb = u.pn * 256 + wc * 32 + 8 * fq;
; #pragma unroll
;         for (int ai = 0; ai < 2; ++ai)
; #pragma unroll
;             for (int m = 0; m < 4; ++m)
; #pragma unroll
;                 for (int bj = 0; bj < 2; ++bj) {
;                     float v[8]; const f32x4 v0 = acc[ai][bj][m][0], v1 = acc[ai][bj][m][1];
;                     v[0] = v0.x; v[1] = v0.y; v[2] = v0.z; v[3] = v0.w; v[4] = v1.x; v[5] = v1.y; v[6] = v1.z; v[7] = v1.w;
;                     emit(row0 + ai * 128 + m * 16, u.pn, colb + bj * 128, v);
;                 }
;     }
.Llo_epi:
	v_lshl_add_u32 v202, s43, 8, v186
	s_lshl_b32 s98, s42, 8
	v_or_b32_e32 v203, s98, v188
	v_mul_u32_u24_e32 v242, 0xc00, v202
	v_lshl_add_u32 v242, v203, 1, v242
	v_mov_b32_e32 v182, v242
	v_add_u32_e32 v183, 0xc000, v242
	v_add_u32_e32 v184, 0x18000, v242
	v_add_u32_e32 v185, 0x24000, v242
	v_add_u32_e32 v190, 0x60000, v242
	v_add_u32_e32 v191, 0x6c000, v242
	v_add_u32_e32 v200, 0x78000, v242
	v_add_u32_e32 v201, 0x84000, v242
	s_cmp_gt_u32 s42, 3
	s_cbranch_scc1 .Llo_raw
	s_mov_b64 s[100:101], s[68:69]
	s_cmp_gt_u32 s42, 1
	s_cbranch_scc0 .Llo_f0
	v_readlane_b32 s100, v255, 19
	v_readlane_b32 s101, v255, 20
	s_add_u32 s100, s100, 0xfffff800
	s_addc_u32 s101, s101, -1
.Llo_f0:
	v_lshlrev_b32_e32 v0, 2, v203
	s_nop 1
	global_load_dwordx4 v[144:147], v0, s[100:101]
	global_load_dwordx4 v[148:151], v0, s[100:101] offset:16
	global_load_dwordx4 v[152:155], v0, s[100:101] offset:512
	global_load_dwordx4 v[156:159], v0, s[100:101] offset:528
	s_waitcnt vmcnt(0)
	v_pk_add_f32 v[128:129], v[128:129], v[144:145]
	v_pk_add_f32 v[130:131], v[130:131], v[146:147]
	v_pk_add_f32 v[124:125], v[124:125], v[148:149]
	v_pk_add_f32 v[126:127], v[126:127], v[150:151]
	v_mul_f32_e32 v128, 0xbfb8aa3b, v128
	v_mul_f32_e32 v129, 0xbfb8aa3b, v129
	v_mul_f32_e32 v130, 0xbfb8aa3b, v130
	v_mul_f32_e32 v131, 0xbfb8aa3b, v131
	v_mul_f32_e32 v124, 0xbfb8aa3b, v124
	v_mul_f32_e32 v125, 0xbfb8aa3b, v125
	v_mul_f32_e32 v126, 0xbfb8aa3b, v126
	v_mul_f32_e32 v127, 0xbfb8aa3b, v127
	v_exp_f32_e32 v128, v128
	v_exp_f32_e32 v129, v129
	v_exp_f32_e32 v130, v130
	v_exp_f32_e32 v131, v131
	v_exp_f32_e32 v124, v124
	v_exp_f32_e32 v125, v125
	v_exp_f32_e32 v126, v126
	v_exp_f32_e32 v127, v127
	v_add_f32_e32 v128, 1.0, v128
	v_add_f32_e32 v129, 1.0, v129
	v_add_f32_e32 v130, 1.0, v130
	v_add_f32_e32 v131, 1.0, v131
	v_add_f32_e32 v124, 1.0, v124
	v_add_f32_e32 v125, 1.0, v125
	v_add_f32_e32 v126, 1.0, v126
	v_add_f32_e32 v127, 1.0, v127
	v_rcp_f32_e32 v128, v128
	v_rcp_f32_e32 v129, v129
	v_rcp_f32_e32 v130, v130
	v_rcp_f32_e32 v131, v131
	v_rcp_f32_e32 v124, v124
	v_rcp_f32_e32 v125, v125
	v_rcp_f32_e32 v126, v126
	v_rcp_f32_e32 v127, v127
	s_cmp_gt_u32 s42, 1
	s_cbranch_scc1 .Llo_ns0
	v_mul_f32_e32 v128, 0x3f1b4598, v128
	v_mul_f32_e32 v129, 0x3f1b4598, v129
	v_mul_f32_e32 v130, 0x3f1b4598, v130
	v_mul_f32_e32 v131, 0x3f1b4598, v131
	v_mul_f32_e32 v124, 0x3f1b4598, v124
	v_mul_f32_e32 v125, 0x3f1b4598, v125
	v_mul_f32_e32 v126, 0x3f1b4598, v126
	v_mul_f32_e32 v127, 0x3f1b4598, v127
.Llo_ns0:
	s_nop 0
	v_cvt_pk_bf16_f32 v244, v128, v129
	v_cvt_pk_bf16_f32 v245, v130, v131
	v_cvt_pk_bf16_f32 v246, v124, v125
	v_cvt_pk_bf16_f32 v247, v126, v127
	global_store_dwordx4 v182, v[244:247], s[44:45]
	v_pk_add_f32 v[120:121], v[120:121], v[152:153]
	v_pk_add_f32 v[122:123], v[122:123], v[154:155]
	v_pk_add_f32 v[116:117], v[116:117], v[156:157]
	v_pk_add_f32 v[118:119], v[118:119], v[158:159]
	v_mul_f32_e32 v120, 0xbfb8aa3b, v120
	v_mul_f32_e32 v121, 0xbfb8aa3b, v121
	v_mul_f32_e32 v122, 0xbfb8aa3b, v122
	v_mul_f32_e32 v123, 0xbfb8aa3b, v123
	v_mul_f32_e32 v116, 0xbfb8aa3b, v116
	v_mul_f32_e32 v117, 0xbfb8aa3b, v117
	v_mul_f32_e32 v118, 0xbfb8aa3b, v118
	v_mul_f32_e32 v119, 0xbfb8aa3b, v119
	v_exp_f32_e32 v120, v120
	v_exp_f32_e32 v121, v121
	v_exp_f32_e32 v122, v122
	v_exp_f32_e32 v123, v123
	v_exp_f32_e32 v116, v116
	v_exp_f32_e32 v117, v117
	v_exp_f32_e32 v118, v118
	v_exp_f32_e32 v119, v119
	v_add_f32_e32 v120, 1.0, v120
	v_add_f32_e32 v121, 1.0, v121
	v_add_f32_e32 v122, 1.0, v122
	v_add_f32_e32 v123, 1.0, v123
	v_add_f32_e32 v116, 1.0, v116
	v_add_f32_e32 v117, 1.0, v117
	v_add_f32_e32 v118, 1.0, v118
	v_add_f32_e32 v119, 1.0, v119
	v_rcp_f32_e32 v120, v120
	v_rcp_f32_e32 v121, v121
	v_rcp_f32_e32 v122, v122
	v_rcp_f32_e32 v123, v123
	v_rcp_f32_e32 v116, v116
	v_rcp_f32_e32 v117, v117
	v_rcp_f32_e32 v118, v118
	v_rcp_f32_e32 v119, v119
	s_cmp_gt_u32 s42, 1
	s_cbranch_scc1 .Llo_ns1
	v_mul_f32_e32 v120, 0x3f1b4598, v120
	v_mul_f32_e32 v121, 0x3f1b4598, v121
	v_mul_f32_e32 v122, 0x3f1b4598, v122
	v_mul_f32_e32 v123, 0x3f1b4598, v123
	v_mul_f32_e32 v116, 0x3f1b4598, v116
	v_mul_f32_e32 v117, 0x3f1b4598, v117
	v_mul_f32_e32 v118, 0x3f1b4598, v118
	v_mul_f32_e32 v119, 0x3f1b4598, v119
.Llo_ns1:
	s_nop 0
	v_cvt_pk_bf16_f32 v248, v120, v121
	v_cvt_pk_bf16_f32 v249, v122, v123
	v_cvt_pk_bf16_f32 v250, v116, v117
	v_cvt_pk_bf16_f32 v251, v118, v119
	global_store_dwordx4 v182, v[248:251], s[44:45] offset:256
	v_pk_add_f32 v[112:113], v[112:113], v[144:145]
	v_pk_add_f32 v[114:115], v[114:115], v[146:147]
	v_pk_add_f32 v[108:109], v[108:109], v[148:149]
	v_pk_add_f32 v[110:111], v[110:111], v[150:151]
	v_mul_f32_e32 v112, 0xbfb8aa3b, v112
	v_mul_f32_e32 v113, 0xbfb8aa3b, v113
	v_mul_f32_e32 v114, 0xbfb8aa3b, v114
	v_mul_f32_e32 v115, 0xbfb8aa3b, v115
	v_mul_f32_e32 v108, 0xbfb8aa3b, v108
	v_mul_f32_e32 v109, 0xbfb8aa3b, v109
	v_mul_f32_e32 v110, 0xbfb8aa3b, v110
	v_mul_f32_e32 v111, 0xbfb8aa3b, v111
	v_exp_f32_e32 v112, v112
	v_exp_f32_e32 v113, v113
	v_exp_f32_e32 v114, v114
	v_exp_f32_e32 v115, v115
	v_exp_f32_e32 v108, v108
	v_exp_f32_e32 v109, v109
	v_exp_f32_e32 v110, v110
	v_exp_f32_e32 v111, v111
	v_add_f32_e32 v112, 1.0, v112
	v_add_f32_e32 v113, 1.0, v113
	v_add_f32_e32 v114, 1.0, v114
	v_add_f32_e32 v115, 1.0, v115
	v_add_f32_e32 v108, 1.0, v108
	v_add_f32_e32 v109, 1.0, v109
	v_add_f32_e32 v110, 1.0, v110
	v_add_f32_e32 v111, 1.0, v111
	v_rcp_f32_e32 v112, v112
	v_rcp_f32_e32 v113, v113
	v_rcp_f32_e32 v114, v114
	v_rcp_f32_e32 v115, v115
	v_rcp_f32_e32 v108, v108
	v_rcp_f32_e32 v109, v109
	v_rcp_f32_e32 v110, v110
	v_rcp_f32_e32 v111, v111
	s_cmp_gt_u32 s42, 1
	s_cbranch_scc1 .Llo_ns2
	v_mul_f32_e32 v112, 0x3f1b4598, v112
	v_mul_f32_e32 v113, 0x3f1b4598, v113
	v_mul_f32_e32 v114, 0x3f1b4598, v114
	v_mul_f32_e32 v115, 0x3f1b4598, v115
	v_mul_f32_e32 v108, 0x3f1b4598, v108
	v_mul_f32_e32 v109, 0x3f1b4598, v109
	v_mul_f32_e32 v110, 0x3f1b4598, v110
	v_mul_f32_e32 v111, 0x3f1b4598, v111
; __device__ __forceinline__ float sigmoidf_(float x) { return __builtin_amdgcn_rcpf(1.f + __expf(-x)); }
;     __device__ __forceinline__ void emit(int row, int pn, int col0, float* v) const {
;     ...
;         case K_LORA: {
;             if (col0 < 512) {
; #pragma unroll
;                 for (int j = 0; j < 8; ++j) v[j] = 0.6065306597126334f * sigmoidf_(v[j] + f0[col0 + j]); }
;             else if (col0 < 1024) {
; #pragma unroll
;                 for (int j = 0; j < 8; ++j) v[j] = sigmoidf_(v[j] + f1[col0 - 512 + j]); }
;             store8((bf16_t*)(ws + WS_WAG) + (size_t)row * 1536 + col0, v);
;         } break;
;     __device__ __forceinline__ void operator()(const f32x4 (&acc)[2][2][4][2], const pg8::Unit& u, int wr, int wc, int fr, int fq) const {
;         const int row0 = u.pm * 256 + wr * 64 + fr, colb = u.pn * 256 + wc * 32 + 8 * fq;
; #pragma unroll
;         for (int ai = 0; ai < 2; ++ai)
; #pragma unroll
;             for (int m = 0; m < 4; ++m)
; #pragma unroll
;                 for (int bj = 0; bj < 2; ++bj) {
;                     float v[8]; const f32x4 v0 = acc[ai][bj][m][0], v1 = acc[ai][bj][m][1];
;                     v[0] = v0.x; v[1] = v0.y; v[2] = v0.z; v[3] = v0.w; v[4] = v1.x; v[5] = v1.y; v[6] = v1.z; v[7] = v1.w;
;                     emit(row0 + ai * 128 + m * 16, u.pn, colb + bj * 128, v);
;                 }
;     }
.Llo_ns2:
	s_nop 0
	v_cvt_pk_bf16_f32 v244, v112, v113
	v_cvt_pk_bf16_f32 v245, v114, v115
	v_cvt_pk_bf16_f32 v246, v108, v109
	v_cvt_pk_bf16_f32 v247, v110, v111
	global_store_dwordx4 v183, v[244:247], s[44:45]
	v_pk_add_f32 v[104:105], v[104:105], v[152:153]
	v_pk_add_f32 v[106:107], v[106:107], v[154:155]
	v_pk_add_f32 v[100:101], v[100:101], v[156:157]
	v_pk_add_f32 v[102:103], v[102:103], v[158:159]
	v_mul_f32_e32 v104, 0xbfb8aa3b, v104
	v_mul_f32_e32 v105, 0xbfb8aa3b, v105
	v_mul_f32_e32 v106, 0xbfb8aa3b, v106
	v_mul_f32_e32 v107, 0xbfb8aa3b, v107
	v_mul_f32_e32 v100, 0xbfb8aa3b, v100
	v_mul_f32_e32 v101, 0xbfb8aa3b, v101
	v_mul_f32_e32 v102, 0xbfb8aa3b, v102
	v_mul_f32_e32 v103, 0xbfb8aa3b, v103
	v_exp_f32_e32 v104, v104
	v_exp_f32_e32 v105, v105
	v_exp_f32_e32 v106, v106
	v_exp_f32_e32 v107, v107
	v_exp_f32_e32 v100, v100
	v_exp_f32_e32 v101, v101
	v_exp_f32_e32 v102, v102
	v_exp_f32_e32 v103, v103
	v_add_f32_e32 v104, 1.0, v104
	v_add_f32_e32 v105, 1.0, v105
	v_add_f32_e32 v106, 1.0, v106
	v_add_f32_e32 v107, 1.0, v107
	v_add_f32_e32 v100, 1.0, v100
	v_add_f32_e32 v101, 1.0, v101
	v_add_f32_e32 v102, 1.0, v102
	v_add_f32_e32 v103, 1.0, v103
	v_rcp_f32_e32 v104, v104
	v_rcp_f32_e32 v105, v105
	v_rcp_f32_e32 v106, v106
	v_rcp_f32_e32 v107, v107
	v_rcp_f32_e32 v100, v100
	v_rcp_f32_e32 v101, v101
	v_rcp_f32_e32 v102, v102
	v_rcp_f32_e32 v103, v103
	s_cmp_gt_u32 s42, 1
	s_cbranch_scc1 .Llo_ns3
	v_mul_f32_e32 v104, 0x3f1b4598, v104
	v_mul_f32_e32 v105, 0x3f1b4598, v105
	v_mul_f32_e32 v106, 0x3f1b4598, v106
	v_mul_f32_e32 v107, 0x3f1b4598, v107
	v_mul_f32_e32 v100, 0x3f1b4598, v100
	v_mul_f32_e32 v101, 0x3f1b4598, v101
	v_mul_f32_e32 v102, 0x3f1b4598, v102
	v_mul_f32_e32 v103, 0x3f1b4598, v103
.Llo_ns3:
	s_nop 0
	v_cvt_pk_bf16_f32 v248, v104, v105
	v_cvt_pk_bf16_f32 v249, v106, v107
	v_cvt_pk_bf16_f32 v250, v100, v101
	v_cvt_pk_bf16_f32 v251, v102, v103
	global_store_dwordx4 v183, v[248:251], s[44:45] offset:256
	v_pk_add_f32 v[96:97], v[96:97], v[144:145]
	v_pk_add_f32 v[98:99], v[98:99], v[146:147]
	v_pk_add_f32 v[92:93], v[92:93], v[148:149]
	v_pk_add_f32 v[94:95], v[94:95], v[150:151]
	v_mul_f32_e32 v96, 0xbfb8aa3b, v96
	v_mul_f32_e32 v97, 0xbfb8aa3b, v97
	v_mul_f32_e32 v98, 0xbfb8aa3b, v98
	v_mul_f32_e32 v99, 0xbfb8aa3b, v99
	v_mul_f32_e32 v92, 0xbfb8aa3b, v92
	v_mul_f32_e32 v93, 0xbfb8aa3b, v93
	v_mul_f32_e32 v94, 0xbfb8aa3b, v94
	v_mul_f32_e32 v95, 0xbfb8aa3b, v95
	v_exp_f32_e32 v96, v96
	v_exp_f32_e32 v97, v97
	v_exp_f32_e32 v98, v98
	v_exp_f32_e32 v99, v99
	v_exp_f32_e32 v92, v92
	v_exp_f32_e32 v93, v93
	v_exp_f32_e32 v94, v94
	v_exp_f32_e32 v95, v95
	v_add_f32_e32 v96, 1.0, v96
	v_add_f32_e32 v97, 1.0, v97
	v_add_f32_e32 v98, 1.0, v98
	v_add_f32_e32 v99, 1.0, v99
	v_add_f32_e32 v92, 1.0, v92
	v_add_f32_e32 v93, 1.0, v93
	v_add_f32_e32 v94, 1.0, v94
	v_add_f32_e32 v95, 1.0, v95
	v_rcp_f32_e32 v96, v96
	v_rcp_f32_e32 v97, v97
	v_rcp_f32_e32 v98, v98
	v_rcp_f32_e32 v99, v99
	v_rcp_f32_e32 v92, v92
	v_rcp_f32_e32 v93, v93
	v_rcp_f32_e32 v94, v94
	v_rcp_f32_e32 v95, v95
	s_cmp_gt_u32 s42, 1
	s_cbranch_scc1 .Llo_ns4
	v_mul_f32_e32 v96, 0x3f1b4598, v96
	v_mul_f32_e32 v97, 0x3f1b4598, v97
	v_mul_f32_e32 v98, 0x3f1b4598, v98
	v_mul_f32_e32 v99, 0x3f1b4598, v99
	v_mul_f32_e32 v92, 0x3f1b4598, v92
	v_mul_f32_e32 v93, 0x3f1b4598, v93
	v_mul_f32_e32 v94, 0x3f1b4598, v94
	v_mul_f32_e32 v95, 0x3f1b4598, v95
.Llo_ns4:
	s_nop 0
	v_cvt_pk_bf16_f32 v244, v96, v97
	v_cvt_pk_bf16_f32 v245, v98, v99
	v_cvt_pk_bf16_f32 v246, v92, v93
	v_cvt_pk_bf16_f32 v247, v94, v95
	global_store_dwordx4 v184, v[244:247], s[44:45]
	v_pk_add_f32 v[88:89], v[88:89], v[152:153]
	v_pk_add_f32 v[90:91], v[90:91], v[154:155]
	v_pk_add_f32 v[84:85], v[84:85], v[156:157]
	v_pk_add_f32 v[86:87], v[86:87], v[158:159]
	v_mul_f32_e32 v88, 0xbfb8aa3b, v88
	v_mul_f32_e32 v89, 0xbfb8aa3b, v89
	v_mul_f32_e32 v90, 0xbfb8aa3b, v90
	v_mul_f32_e32 v91, 0xbfb8aa3b, v91
	v_mul_f32_e32 v84, 0xbfb8aa3b, v84
	v_mul_f32_e32 v85, 0xbfb8aa3b, v85
	v_mul_f32_e32 v86, 0xbfb8aa3b, v86
	v_mul_f32_e32 v87, 0xbfb8aa3b, v87
	v_exp_f32_e32 v88, v88
	v_exp_f32_e32 v89, v89
	v_exp_f32_e32 v90, v90
	v_exp_f32_e32 v91, v91
	v_exp_f32_e32 v84, v84
	v_exp_f32_e32 v85, v85
	v_exp_f32_e32 v86, v86
	v_exp_f32_e32 v87, v87
	v_add_f32_e32 v88, 1.0, v88
	v_add_f32_e32 v89, 1.0, v89
	v_add_f32_e32 v90, 1.0, v90
	v_add_f32_e32 v91, 1.0, v91
	v_add_f32_e32 v84, 1.0, v84
	v_add_f32_e32 v85, 1.0, v85
	v_add_f32_e32 v86, 1.0, v86
	v_add_f32_e32 v87, 1.0, v87
	v_rcp_f32_e32 v88, v88
	v_rcp_f32_e32 v89, v89
	v_rcp_f32_e32 v90, v90
	v_rcp_f32_e32 v91, v91
	v_rcp_f32_e32 v84, v84
	v_rcp_f32_e32 v85, v85
	v_rcp_f32_e32 v86, v86
	v_rcp_f32_e32 v87, v87
	s_cmp_gt_u32 s42, 1
	s_cbranch_scc1 .Llo_ns5
	v_mul_f32_e32 v88, 0x3f1b4598, v88
	v_mul_f32_e32 v89, 0x3f1b4598, v89
	v_mul_f32_e32 v90, 0x3f1b4598, v90
	v_mul_f32_e32 v91, 0x3f1b4598, v91
	v_mul_f32_e32 v84, 0x3f1b4598, v84
	v_mul_f32_e32 v85, 0x3f1b4598, v85
	v_mul_f32_e32 v86, 0x3f1b4598, v86
	v_mul_f32_e32 v87, 0x3f1b4598, v87
; __device__ __forceinline__ float sigmoidf_(float x) { return __builtin_amdgcn_rcpf(1.f + __expf(-x)); }
;     __device__ __forceinline__ void emit(int row, int pn, int col0, float* v) const {
;     ...
;         case K_LORA: {
;             if (col0 < 512) {
; #pragma unroll
;                 for (int j = 0; j < 8; ++j) v[j] = 0.6065306597126334f * sigmoidf_(v[j] + f0[col0 + j]); }
;             else if (col0 < 1024) {
; #pragma unroll
;                 for (int j = 0; j < 8; ++j) v[j] = sigmoidf_(v[j] + f1[col0 - 512 + j]); }
;             store8((bf16_t*)(ws + WS_WAG) + (size_t)row * 1536 + col0, v);
;         } break;
;     __device__ __forceinline__ void operator()(const f32x4 (&acc)[2][2][4][2], const pg8::Unit& u, int wr, int wc, int fr, int fq) const {
;         const int row0 = u.pm * 256 + wr * 64 + fr, colb = u.pn * 256 + wc * 32 + 8 * fq;
; #pragma unroll
;         for (int ai = 0; ai < 2; ++ai)
; #pragma unroll
;             for (int m = 0; m < 4; ++m)
; #pragma unroll
;                 for (int bj = 0; bj < 2; ++bj) {
;                     float v[8]; const f32x4 v0 = acc[ai][bj][m][0], v1 = acc[ai][bj][m][1];
;                     v[0] = v0.x; v[1] = v0.y; v[2] = v0.z; v[3] = v0.w; v[4] = v1.x; v[5] = v1.y; v[6] = v1.z; v[7] = v1.w;
;                     emit(row0 + ai * 128 + m * 16, u.pn, colb + bj * 128, v);
;                 }
;     }
.Llo_ns5:
	s_nop 0
	v_cvt_pk_bf16_f32 v248, v88, v89
	v_cvt_pk_bf16_f32 v249, v90, v91
	v_cvt_pk_bf16_f32 v250, v84, v85
	v_cvt_pk_bf16_f32 v251, v86, v87
	global_store_dwordx4 v184, v[248:251], s[44:45] offset:256
	v_pk_add_f32 v[80:81], v[80:81], v[144:145]
	v_pk_add_f32 v[82:83], v[82:83], v[146:147]
	v_pk_add_f32 v[76:77], v[76:77], v[148:149]
	v_pk_add_f32 v[78:79], v[78:79], v[150:151]
	v_mul_f32_e32 v80, 0xbfb8aa3b, v80
	v_mul_f32_e32 v81, 0xbfb8aa3b, v81
	v_mul_f32_e32 v82, 0xbfb8aa3b, v82
	v_mul_f32_e32 v83, 0xbfb8aa3b, v83
	v_mul_f32_e32 v76, 0xbfb8aa3b, v76
	v_mul_f32_e32 v77, 0xbfb8aa3b, v77
	v_mul_f32_e32 v78, 0xbfb8aa3b, v78
	v_mul_f32_e32 v79, 0xbfb8aa3b, v79
	v_exp_f32_e32 v80, v80
	v_exp_f32_e32 v81, v81
	v_exp_f32_e32 v82, v82
	v_exp_f32_e32 v83, v83
	v_exp_f32_e32 v76, v76
	v_exp_f32_e32 v77, v77
	v_exp_f32_e32 v78, v78
	v_exp_f32_e32 v79, v79
	v_add_f32_e32 v80, 1.0, v80
	v_add_f32_e32 v81, 1.0, v81
	v_add_f32_e32 v82, 1.0, v82
	v_add_f32_e32 v83, 1.0, v83
	v_add_f32_e32 v76, 1.0, v76
	v_add_f32_e32 v77, 1.0, v77
	v_add_f32_e32 v78, 1.0, v78
	v_add_f32_e32 v79, 1.0, v79
	v_rcp_f32_e32 v80, v80
	v_rcp_f32_e32 v81, v81
	v_rcp_f32_e32 v82, v82
	v_rcp_f32_e32 v83, v83
	v_rcp_f32_e32 v76, v76
	v_rcp_f32_e32 v77, v77
	v_rcp_f32_e32 v78, v78
	v_rcp_f32_e32 v79, v79
	s_cmp_gt_u32 s42, 1
	s_cbranch_scc1 .Llo_ns6
	v_mul_f32_e32 v80, 0x3f1b4598, v80
	v_mul_f32_e32 v81, 0x3f1b4598, v81
	v_mul_f32_e32 v82, 0x3f1b4598, v82
	v_mul_f32_e32 v83, 0x3f1b4598, v83
	v_mul_f32_e32 v76, 0x3f1b4598, v76
	v_mul_f32_e32 v77, 0x3f1b4598, v77
	v_mul_f32_e32 v78, 0x3f1b4598, v78
	v_mul_f32_e32 v79, 0x3f1b4598, v79
.Llo_ns6:
	s_nop 0
	v_cvt_pk_bf16_f32 v244, v80, v81
	v_cvt_pk_bf16_f32 v245, v82, v83
	v_cvt_pk_bf16_f32 v246, v76, v77
	v_cvt_pk_bf16_f32 v247, v78, v79
	global_store_dwordx4 v185, v[244:247], s[44:45]
	v_pk_add_f32 v[72:73], v[72:73], v[152:153]
	v_pk_add_f32 v[74:75], v[74:75], v[154:155]
	v_pk_add_f32 v[68:69], v[68:69], v[156:157]
	v_pk_add_f32 v[70:71], v[70:71], v[158:159]
	v_mul_f32_e32 v72, 0xbfb8aa3b, v72
	v_mul_f32_e32 v73, 0xbfb8aa3b, v73
	v_mul_f32_e32 v74, 0xbfb8aa3b, v74
	v_mul_f32_e32 v75, 0xbfb8aa3b, v75
	v_mul_f32_e32 v68, 0xbfb8aa3b, v68
	v_mul_f32_e32 v69, 0xbfb8aa3b, v69
	v_mul_f32_e32 v70, 0xbfb8aa3b, v70
	v_mul_f32_e32 v71, 0xbfb8aa3b, v71
	v_exp_f32_e32 v72, v72
	v_exp_f32_e32 v73, v73
	v_exp_f32_e32 v74, v74
	v_exp_f32_e32 v75, v75
	v_exp_f32_e32 v68, v68
	v_exp_f32_e32 v69, v69
	v_exp_f32_e32 v70, v70
	v_exp_f32_e32 v71, v71
	v_add_f32_e32 v72, 1.0, v72
	v_add_f32_e32 v73, 1.0, v73
	v_add_f32_e32 v74, 1.0, v74
	v_add_f32_e32 v75, 1.0, v75
	v_add_f32_e32 v68, 1.0, v68
	v_add_f32_e32 v69, 1.0, v69
	v_add_f32_e32 v70, 1.0, v70
	v_add_f32_e32 v71, 1.0, v71
	v_rcp_f32_e32 v72, v72
	v_rcp_f32_e32 v73, v73
	v_rcp_f32_e32 v74, v74
	v_rcp_f32_e32 v75, v75
	v_rcp_f32_e32 v68, v68
	v_rcp_f32_e32 v69, v69
	v_rcp_f32_e32 v70, v70
	v_rcp_f32_e32 v71, v71
	s_cmp_gt_u32 s42, 1
	s_cbranch_scc1 .Llo_ns7
	v_mul_f32_e32 v72, 0x3f1b4598, v72
	v_mul_f32_e32 v73, 0x3f1b4598, v73
	v_mul_f32_e32 v74, 0x3f1b4598, v74
	v_mul_f32_e32 v75, 0x3f1b4598, v75
	v_mul_f32_e32 v68, 0x3f1b4598, v68
	v_mul_f32_e32 v69, 0x3f1b4598, v69
	v_mul_f32_e32 v70, 0x3f1b4598, v70
	v_mul_f32_e32 v71, 0x3f1b4598, v71
.Llo_ns7:
	s_nop 0
	v_cvt_pk_bf16_f32 v248, v72, v73
	v_cvt_pk_bf16_f32 v249, v74, v75
	v_cvt_pk_bf16_f32 v250, v68, v69
	v_cvt_pk_bf16_f32 v251, v70, v71
	global_store_dwordx4 v185, v[248:251], s[44:45] offset:256
	v_pk_add_f32 v[64:65], v[64:65], v[144:145]
	v_pk_add_f32 v[66:67], v[66:67], v[146:147]
	v_pk_add_f32 v[60:61], v[60:61], v[148:149]
	v_pk_add_f32 v[62:63], v[62:63], v[150:151]
	v_mul_f32_e32 v64, 0xbfb8aa3b, v64
	v_mul_f32_e32 v65, 0xbfb8aa3b, v65
	v_mul_f32_e32 v66, 0xbfb8aa3b, v66
	v_mul_f32_e32 v67, 0xbfb8aa3b, v67
	v_mul_f32_e32 v60, 0xbfb8aa3b, v60
	v_mul_f32_e32 v61, 0xbfb8aa3b, v61
	v_mul_f32_e32 v62, 0xbfb8aa3b, v62
	v_mul_f32_e32 v63, 0xbfb8aa3b, v63
	v_exp_f32_e32 v64, v64
	v_exp_f32_e32 v65, v65
	v_exp_f32_e32 v66, v66
	v_exp_f32_e32 v67, v67
	v_exp_f32_e32 v60, v60
	v_exp_f32_e32 v61, v61
	v_exp_f32_e32 v62, v62
	v_exp_f32_e32 v63, v63
	v_add_f32_e32 v64, 1.0, v64
	v_add_f32_e32 v65, 1.0, v65
	v_add_f32_e32 v66, 1.0, v66
	v_add_f32_e32 v67, 1.0, v67
	v_add_f32_e32 v60, 1.0, v60
	v_add_f32_e32 v61, 1.0, v61
	v_add_f32_e32 v62, 1.0, v62
	v_add_f32_e32 v63, 1.0, v63
	v_rcp_f32_e32 v64, v64
	v_rcp_f32_e32 v65, v65
	v_rcp_f32_e32 v66, v66
	v_rcp_f32_e32 v67, v67
	v_rcp_f32_e32 v60, v60
	v_rcp_f32_e32 v61, v61
	v_rcp_f32_e32 v62, v62
	v_rcp_f32_e32 v63, v63
	s_cmp_gt_u32 s42, 1
	s_cbranch_scc1 .Llo_ns8
	v_mul_f32_e32 v64, 0x3f1b4598, v64
	v_mul_f32_e32 v65, 0x3f1b4598, v65
	v_mul_f32_e32 v66, 0x3f1b4598, v66
	v_mul_f32_e32 v67, 0x3f1b4598, v67
	v_mul_f32_e32 v60, 0x3f1b4598, v60
	v_mul_f32_e32 v61, 0x3f1b4598, v61
	v_mul_f32_e32 v62, 0x3f1b4598, v62
	v_mul_f32_e32 v63, 0x3f1b4598, v63
; __device__ __forceinline__ float sigmoidf_(float x) { return __builtin_amdgcn_rcpf(1.f + __expf(-x)); }
;     __device__ __forceinline__ void emit(int row, int pn, int col0, float* v) const {
;     ...
;         case K_LORA: {
;             if (col0 < 512) {
; #pragma unroll
;                 for (int j = 0; j < 8; ++j) v[j] = 0.6065306597126334f * sigmoidf_(v[j] + f0[col0 + j]); }
;             else if (col0 < 1024) {
; #pragma unroll
;                 for (int j = 0; j < 8; ++j) v[j] = sigmoidf_(v[j] + f1[col0 - 512 + j]); }
;             store8((bf16_t*)(ws + WS_WAG) + (size_t)row * 1536 + col0, v);
;         } break;
;     __device__ __forceinline__ void operator()(const f32x4 (&acc)[2][2][4][2], const pg8::Unit& u, int wr, int wc, int fr, int fq) const {
;         const int row0 = u.pm * 256 + wr * 64 + fr, colb = u.pn * 256 + wc * 32 + 8 * fq;
; #pragma unroll
;         for (int ai = 0; ai < 2; ++ai)
; #pragma unroll
;             for (int m = 0; m < 4; ++m)
; #pragma unroll
;                 for (int bj = 0; bj < 2; ++bj) {
;                     float v[8]; const f32x4 v0 = acc[ai][bj][m][0], v1 = acc[ai][bj][m][1];
;                     v[0] = v0.x; v[1] = v0.y; v[2] = v0.z; v[3] = v0.w; v[4] = v1.x; v[5] = v1.y; v[6] = v1.z; v[7] = v1.w;
;                     emit(row0 + ai * 128 + m * 16, u.pn, colb + bj * 128, v);
;                 }
;     }
.Llo_ns8:
	s_nop 0
	v_cvt_pk_bf16_f32 v244, v64, v65
	v_cvt_pk_bf16_f32 v245, v66, v67
	v_cvt_pk_bf16_f32 v246, v60, v61
	v_cvt_pk_bf16_f32 v247, v62, v63
	global_store_dwordx4 v190, v[244:247], s[44:45]
	v_pk_add_f32 v[56:57], v[56:57], v[152:153]
	v_pk_add_f32 v[58:59], v[58:59], v[154:155]
	v_pk_add_f32 v[52:53], v[52:53], v[156:157]
	v_pk_add_f32 v[54:55], v[54:55], v[158:159]
	v_mul_f32_e32 v56, 0xbfb8aa3b, v56
	v_mul_f32_e32 v57, 0xbfb8aa3b, v57
	v_mul_f32_e32 v58, 0xbfb8aa3b, v58
	v_mul_f32_e32 v59, 0xbfb8aa3b, v59
	v_mul_f32_e32 v52, 0xbfb8aa3b, v52
	v_mul_f32_e32 v53, 0xbfb8aa3b, v53
	v_mul_f32_e32 v54, 0xbfb8aa3b, v54
	v_mul_f32_e32 v55, 0xbfb8aa3b, v55
	v_exp_f32_e32 v56, v56
	v_exp_f32_e32 v57, v57
	v_exp_f32_e32 v58, v58
	v_exp_f32_e32 v59, v59
	v_exp_f32_e32 v52, v52
	v_exp_f32_e32 v53, v53
	v_exp_f32_e32 v54, v54
	v_exp_f32_e32 v55, v55
	v_add_f32_e32 v56, 1.0, v56
	v_add_f32_e32 v57, 1.0, v57
	v_add_f32_e32 v58, 1.0, v58
	v_add_f32_e32 v59, 1.0, v59
	v_add_f32_e32 v52, 1.0, v52
	v_add_f32_e32 v53, 1.0, v53
	v_add_f32_e32 v54, 1.0, v54
	v_add_f32_e32 v55, 1.0, v55
	v_rcp_f32_e32 v56, v56
	v_rcp_f32_e32 v57, v57
	v_rcp_f32_e32 v58, v58
	v_rcp_f32_e32 v59, v59
	v_rcp_f32_e32 v52, v52
	v_rcp_f32_e32 v53, v53
	v_rcp_f32_e32 v54, v54
	v_rcp_f32_e32 v55, v55
	s_cmp_gt_u32 s42, 1
	s_cbranch_scc1 .Llo_ns9
	v_mul_f32_e32 v56, 0x3f1b4598, v56
	v_mul_f32_e32 v57, 0x3f1b4598, v57
	v_mul_f32_e32 v58, 0x3f1b4598, v58
	v_mul_f32_e32 v59, 0x3f1b4598, v59
	v_mul_f32_e32 v52, 0x3f1b4598, v52
	v_mul_f32_e32 v53, 0x3f1b4598, v53
	v_mul_f32_e32 v54, 0x3f1b4598, v54
	v_mul_f32_e32 v55, 0x3f1b4598, v55
.Llo_ns9:
	s_nop 0
	v_cvt_pk_bf16_f32 v248, v56, v57
	v_cvt_pk_bf16_f32 v249, v58, v59
	v_cvt_pk_bf16_f32 v250, v52, v53
	v_cvt_pk_bf16_f32 v251, v54, v55
	global_store_dwordx4 v190, v[248:251], s[44:45] offset:256
	v_pk_add_f32 v[48:49], v[48:49], v[144:145]
	v_pk_add_f32 v[50:51], v[50:51], v[146:147]
	v_pk_add_f32 v[44:45], v[44:45], v[148:149]
	v_pk_add_f32 v[46:47], v[46:47], v[150:151]
	v_mul_f32_e32 v48, 0xbfb8aa3b, v48
	v_mul_f32_e32 v49, 0xbfb8aa3b, v49
	v_mul_f32_e32 v50, 0xbfb8aa3b, v50
	v_mul_f32_e32 v51, 0xbfb8aa3b, v51
	v_mul_f32_e32 v44, 0xbfb8aa3b, v44
	v_mul_f32_e32 v45, 0xbfb8aa3b, v45
	v_mul_f32_e32 v46, 0xbfb8aa3b, v46
	v_mul_f32_e32 v47, 0xbfb8aa3b, v47
	v_exp_f32_e32 v48, v48
	v_exp_f32_e32 v49, v49
	v_exp_f32_e32 v50, v50
	v_exp_f32_e32 v51, v51
	v_exp_f32_e32 v44, v44
	v_exp_f32_e32 v45, v45
	v_exp_f32_e32 v46, v46
	v_exp_f32_e32 v47, v47
	v_add_f32_e32 v48, 1.0, v48
	v_add_f32_e32 v49, 1.0, v49
	v_add_f32_e32 v50, 1.0, v50
	v_add_f32_e32 v51, 1.0, v51
	v_add_f32_e32 v44, 1.0, v44
	v_add_f32_e32 v45, 1.0, v45
	v_add_f32_e32 v46, 1.0, v46
	v_add_f32_e32 v47, 1.0, v47
	v_rcp_f32_e32 v48, v48
	v_rcp_f32_e32 v49, v49
	v_rcp_f32_e32 v50, v50
	v_rcp_f32_e32 v51, v51
	v_rcp_f32_e32 v44, v44
	v_rcp_f32_e32 v45, v45
	v_rcp_f32_e32 v46, v46
	v_rcp_f32_e32 v47, v47
	s_cmp_gt_u32 s42, 1
	s_cbranch_scc1 .Llo_ns10
	v_mul_f32_e32 v48, 0x3f1b4598, v48
	v_mul_f32_e32 v49, 0x3f1b4598, v49
	v_mul_f32_e32 v50, 0x3f1b4598, v50
	v_mul_f32_e32 v51, 0x3f1b4598, v51
	v_mul_f32_e32 v44, 0x3f1b4598, v44
	v_mul_f32_e32 v45, 0x3f1b4598, v45
	v_mul_f32_e32 v46, 0x3f1b4598, v46
	v_mul_f32_e32 v47, 0x3f1b4598, v47
.Llo_ns10:
	s_nop 0
	v_cvt_pk_bf16_f32 v244, v48, v49
	v_cvt_pk_bf16_f32 v245, v50, v51
	v_cvt_pk_bf16_f32 v246, v44, v45
	v_cvt_pk_bf16_f32 v247, v46, v47
	global_store_dwordx4 v191, v[244:247], s[44:45]
	v_pk_add_f32 v[40:41], v[40:41], v[152:153]
	v_pk_add_f32 v[42:43], v[42:43], v[154:155]
	v_pk_add_f32 v[36:37], v[36:37], v[156:157]
	v_pk_add_f32 v[38:39], v[38:39], v[158:159]
	v_mul_f32_e32 v40, 0xbfb8aa3b, v40
	v_mul_f32_e32 v41, 0xbfb8aa3b, v41
	v_mul_f32_e32 v42, 0xbfb8aa3b, v42
	v_mul_f32_e32 v43, 0xbfb8aa3b, v43
	v_mul_f32_e32 v36, 0xbfb8aa3b, v36
	v_mul_f32_e32 v37, 0xbfb8aa3b, v37
	v_mul_f32_e32 v38, 0xbfb8aa3b, v38
	v_mul_f32_e32 v39, 0xbfb8aa3b, v39
	v_exp_f32_e32 v40, v40
	v_exp_f32_e32 v41, v41
	v_exp_f32_e32 v42, v42
	v_exp_f32_e32 v43, v43
	v_exp_f32_e32 v36, v36
	v_exp_f32_e32 v37, v37
	v_exp_f32_e32 v38, v38
	v_exp_f32_e32 v39, v39
	v_add_f32_e32 v40, 1.0, v40
	v_add_f32_e32 v41, 1.0, v41
	v_add_f32_e32 v42, 1.0, v42
	v_add_f32_e32 v43, 1.0, v43
	v_add_f32_e32 v36, 1.0, v36
	v_add_f32_e32 v37, 1.0, v37
	v_add_f32_e32 v38, 1.0, v38
	v_add_f32_e32 v39, 1.0, v39
	v_rcp_f32_e32 v40, v40
	v_rcp_f32_e32 v41, v41
	v_rcp_f32_e32 v42, v42
	v_rcp_f32_e32 v43, v43
	v_rcp_f32_e32 v36, v36
	v_rcp_f32_e32 v37, v37
	v_rcp_f32_e32 v38, v38
	v_rcp_f32_e32 v39, v39
	s_cmp_gt_u32 s42, 1
	s_cbranch_scc1 .Llo_ns11
	v_mul_f32_e32 v40, 0x3f1b4598, v40
	v_mul_f32_e32 v41, 0x3f1b4598, v41
	v_mul_f32_e32 v42, 0x3f1b4598, v42
	v_mul_f32_e32 v43, 0x3f1b4598, v43
	v_mul_f32_e32 v36, 0x3f1b4598, v36
	v_mul_f32_e32 v37, 0x3f1b4598, v37
	v_mul_f32_e32 v38, 0x3f1b4598, v38
	v_mul_f32_e32 v39, 0x3f1b4598, v39
; __device__ __forceinline__ float sigmoidf_(float x) { return __builtin_amdgcn_rcpf(1.f + __expf(-x)); }
;     __device__ __forceinline__ void emit(int row, int pn, int col0, float* v) const {
;     ...
;         case K_LORA: {
;             if (col0 < 512) {
; #pragma unroll
;                 for (int j = 0; j < 8; ++j) v[j] = 0.6065306597126334f * sigmoidf_(v[j] + f0[col0 + j]); }
;             else if (col0 < 1024) {
; #pragma unroll
;                 for (int j = 0; j < 8; ++j) v[j] = sigmoidf_(v[j] + f1[col0 - 512 + j]); }
;             store8((bf16_t*)(ws + WS_WAG) + (size_t)row * 1536 + col0, v);
;         } break;
;     __device__ __forceinline__ void operator()(const f32x4 (&acc)[2][2][4][2], const pg8::Unit& u, int wr, int wc, int fr, int fq) const {
;         const int row0 = u.pm * 256 + wr * 64 + fr, colb = u.pn * 256 + wc * 32 + 8 * fq;
; #pragma unroll
;         for (int ai = 0; ai < 2; ++ai)
; #pragma unroll
;             for (int m = 0; m < 4; ++m)
; #pragma unroll
;                 for (int bj = 0; bj < 2; ++bj) {
;                     float v[8]; const f32x4 v0 = acc[ai][bj][m][0], v1 = acc[ai][bj][m][1];
;                     v[0] = v0.x; v[1] = v0.y; v[2] = v0.z; v[3] = v0.w; v[4] = v1.x; v[5] = v1.y; v[6] = v1.z; v[7] = v1.w;
;                     emit(row0 + ai * 128 + m * 16, u.pn, colb + bj * 128, v);
;                 }
;     }
.Llo_ns11:
	s_nop 0
	v_cvt_pk_bf16_f32 v248, v40, v41
	v_cvt_pk_bf16_f32 v249, v42, v43
	v_cvt_pk_bf16_f32 v250, v36, v37
	v_cvt_pk_bf16_f32 v251, v38, v39
	global_store_dwordx4 v191, v[248:251], s[44:45] offset:256
	v_pk_add_f32 v[32:33], v[32:33], v[144:145]
	v_pk_add_f32 v[34:35], v[34:35], v[146:147]
	v_pk_add_f32 v[28:29], v[28:29], v[148:149]
	v_pk_add_f32 v[30:31], v[30:31], v[150:151]
	v_mul_f32_e32 v32, 0xbfb8aa3b, v32
	v_mul_f32_e32 v33, 0xbfb8aa3b, v33
	v_mul_f32_e32 v34, 0xbfb8aa3b, v34
	v_mul_f32_e32 v35, 0xbfb8aa3b, v35
	v_mul_f32_e32 v28, 0xbfb8aa3b, v28
	v_mul_f32_e32 v29, 0xbfb8aa3b, v29
	v_mul_f32_e32 v30, 0xbfb8aa3b, v30
	v_mul_f32_e32 v31, 0xbfb8aa3b, v31
	v_exp_f32_e32 v32, v32
	v_exp_f32_e32 v33, v33
	v_exp_f32_e32 v34, v34
	v_exp_f32_e32 v35, v35
	v_exp_f32_e32 v28, v28
	v_exp_f32_e32 v29, v29
	v_exp_f32_e32 v30, v30
	v_exp_f32_e32 v31, v31
	v_add_f32_e32 v32, 1.0, v32
	v_add_f32_e32 v33, 1.0, v33
	v_add_f32_e32 v34, 1.0, v34
	v_add_f32_e32 v35, 1.0, v35
	v_add_f32_e32 v28, 1.0, v28
	v_add_f32_e32 v29, 1.0, v29
	v_add_f32_e32 v30, 1.0, v30
	v_add_f32_e32 v31, 1.0, v31
	v_rcp_f32_e32 v32, v32
	v_rcp_f32_e32 v33, v33
	v_rcp_f32_e32 v34, v34
	v_rcp_f32_e32 v35, v35
	v_rcp_f32_e32 v28, v28
	v_rcp_f32_e32 v29, v29
	v_rcp_f32_e32 v30, v30
	v_rcp_f32_e32 v31, v31
	s_cmp_gt_u32 s42, 1
	s_cbranch_scc1 .Llo_ns12
	v_mul_f32_e32 v32, 0x3f1b4598, v32
	v_mul_f32_e32 v33, 0x3f1b4598, v33
	v_mul_f32_e32 v34, 0x3f1b4598, v34
	v_mul_f32_e32 v35, 0x3f1b4598, v35
	v_mul_f32_e32 v28, 0x3f1b4598, v28
	v_mul_f32_e32 v29, 0x3f1b4598, v29
	v_mul_f32_e32 v30, 0x3f1b4598, v30
	v_mul_f32_e32 v31, 0x3f1b4598, v31
.Llo_ns12:
	s_nop 0
	v_cvt_pk_bf16_f32 v244, v32, v33
	v_cvt_pk_bf16_f32 v245, v34, v35
	v_cvt_pk_bf16_f32 v246, v28, v29
	v_cvt_pk_bf16_f32 v247, v30, v31
	global_store_dwordx4 v200, v[244:247], s[44:45]
	v_pk_add_f32 v[24:25], v[24:25], v[152:153]
	v_pk_add_f32 v[26:27], v[26:27], v[154:155]
	v_pk_add_f32 v[20:21], v[20:21], v[156:157]
	v_pk_add_f32 v[22:23], v[22:23], v[158:159]
	v_mul_f32_e32 v24, 0xbfb8aa3b, v24
	v_mul_f32_e32 v25, 0xbfb8aa3b, v25
	v_mul_f32_e32 v26, 0xbfb8aa3b, v26
	v_mul_f32_e32 v27, 0xbfb8aa3b, v27
	v_mul_f32_e32 v20, 0xbfb8aa3b, v20
	v_mul_f32_e32 v21, 0xbfb8aa3b, v21
	v_mul_f32_e32 v22, 0xbfb8aa3b, v22
	v_mul_f32_e32 v23, 0xbfb8aa3b, v23
	v_exp_f32_e32 v24, v24
	v_exp_f32_e32 v25, v25
	v_exp_f32_e32 v26, v26
	v_exp_f32_e32 v27, v27
	v_exp_f32_e32 v20, v20
	v_exp_f32_e32 v21, v21
	v_exp_f32_e32 v22, v22
	v_exp_f32_e32 v23, v23
	v_add_f32_e32 v24, 1.0, v24
	v_add_f32_e32 v25, 1.0, v25
	v_add_f32_e32 v26, 1.0, v26
	v_add_f32_e32 v27, 1.0, v27
	v_add_f32_e32 v20, 1.0, v20
	v_add_f32_e32 v21, 1.0, v21
	v_add_f32_e32 v22, 1.0, v22
	v_add_f32_e32 v23, 1.0, v23
	v_rcp_f32_e32 v24, v24
	v_rcp_f32_e32 v25, v25
	v_rcp_f32_e32 v26, v26
	v_rcp_f32_e32 v27, v27
	v_rcp_f32_e32 v20, v20
	v_rcp_f32_e32 v21, v21
	v_rcp_f32_e32 v22, v22
	v_rcp_f32_e32 v23, v23
	s_cmp_gt_u32 s42, 1
	s_cbranch_scc1 .Llo_ns13
	v_mul_f32_e32 v24, 0x3f1b4598, v24
	v_mul_f32_e32 v25, 0x3f1b4598, v25
	v_mul_f32_e32 v26, 0x3f1b4598, v26
	v_mul_f32_e32 v27, 0x3f1b4598, v27
	v_mul_f32_e32 v20, 0x3f1b4598, v20
	v_mul_f32_e32 v21, 0x3f1b4598, v21
	v_mul_f32_e32 v22, 0x3f1b4598, v22
	v_mul_f32_e32 v23, 0x3f1b4598, v23
.Llo_ns13:
	s_nop 0
	v_cvt_pk_bf16_f32 v248, v24, v25
	v_cvt_pk_bf16_f32 v249, v26, v27
	v_cvt_pk_bf16_f32 v250, v20, v21
	v_cvt_pk_bf16_f32 v251, v22, v23
	global_store_dwordx4 v200, v[248:251], s[44:45] offset:256
	v_pk_add_f32 v[16:17], v[16:17], v[144:145]
	v_pk_add_f32 v[18:19], v[18:19], v[146:147]
	v_pk_add_f32 v[12:13], v[12:13], v[148:149]
	v_pk_add_f32 v[14:15], v[14:15], v[150:151]
	v_mul_f32_e32 v16, 0xbfb8aa3b, v16
	v_mul_f32_e32 v17, 0xbfb8aa3b, v17
	v_mul_f32_e32 v18, 0xbfb8aa3b, v18
	v_mul_f32_e32 v19, 0xbfb8aa3b, v19
	v_mul_f32_e32 v12, 0xbfb8aa3b, v12
	v_mul_f32_e32 v13, 0xbfb8aa3b, v13
	v_mul_f32_e32 v14, 0xbfb8aa3b, v14
	v_mul_f32_e32 v15, 0xbfb8aa3b, v15
	v_exp_f32_e32 v16, v16
	v_exp_f32_e32 v17, v17
	v_exp_f32_e32 v18, v18
	v_exp_f32_e32 v19, v19
	v_exp_f32_e32 v12, v12
	v_exp_f32_e32 v13, v13
	v_exp_f32_e32 v14, v14
	v_exp_f32_e32 v15, v15
	v_add_f32_e32 v16, 1.0, v16
	v_add_f32_e32 v17, 1.0, v17
	v_add_f32_e32 v18, 1.0, v18
	v_add_f32_e32 v19, 1.0, v19
	v_add_f32_e32 v12, 1.0, v12
	v_add_f32_e32 v13, 1.0, v13
	v_add_f32_e32 v14, 1.0, v14
	v_add_f32_e32 v15, 1.0, v15
	v_rcp_f32_e32 v16, v16
	v_rcp_f32_e32 v17, v17
	v_rcp_f32_e32 v18, v18
	v_rcp_f32_e32 v19, v19
	v_rcp_f32_e32 v12, v12
	v_rcp_f32_e32 v13, v13
	v_rcp_f32_e32 v14, v14
	v_rcp_f32_e32 v15, v15
	s_cmp_gt_u32 s42, 1
	s_cbranch_scc1 .Llo_ns14
	v_mul_f32_e32 v16, 0x3f1b4598, v16
	v_mul_f32_e32 v17, 0x3f1b4598, v17
	v_mul_f32_e32 v18, 0x3f1b4598, v18
	v_mul_f32_e32 v19, 0x3f1b4598, v19
	v_mul_f32_e32 v12, 0x3f1b4598, v12
	v_mul_f32_e32 v13, 0x3f1b4598, v13
	v_mul_f32_e32 v14, 0x3f1b4598, v14
	v_mul_f32_e32 v15, 0x3f1b4598, v15
; __device__ __forceinline__ float sigmoidf_(float x) { return __builtin_amdgcn_rcpf(1.f + __expf(-x)); }
;     __device__ __forceinline__ void emit(int row, int pn, int col0, float* v) const {
;     ...
;         case K_LORA: {
;             if (col0 < 512) {
; #pragma unroll
;                 for (int j = 0; j < 8; ++j) v[j] = 0.6065306597126334f * sigmoidf_(v[j] + f0[col0 + j]); }
;             else if (col0 < 1024) {
; #pragma unroll
;                 for (int j = 0; j < 8; ++j) v[j] = sigmoidf_(v[j] + f1[col0 - 512 + j]); }
;             store8((bf16_t*)(ws + WS_WAG) + (size_t)row * 1536 + col0, v);
;         } break;
;     __device__ __forceinline__ void operator()(const f32x4 (&acc)[2][2][4][2], const pg8::Unit& u, int wr, int wc, int fr, int fq) const {
;         const int row0 = u.pm * 256 + wr * 64 + fr, colb = u.pn * 256 + wc * 32 + 8 * fq;
; #pragma unroll
;         for (int ai = 0; ai < 2; ++ai)
; #pragma unroll
;             for (int m = 0; m < 4; ++m)
; #pragma unroll
;                 for (int bj = 0; bj < 2; ++bj) {
;                     float v[8]; const f32x4 v0 = acc[ai][bj][m][0], v1 = acc[ai][bj][m][1];
;                     v[0] = v0.x; v[1] = v0.y; v[2] = v0.z; v[3] = v0.w; v[4] = v1.x; v[5] = v1.y; v[6] = v1.z; v[7] = v1.w;
;                     emit(row0 + ai * 128 + m * 16, u.pn, colb + bj * 128, v);
;                 }
;     }
.Llo_ns14:
	s_nop 0
	v_cvt_pk_bf16_f32 v244, v16, v17
	v_cvt_pk_bf16_f32 v245, v18, v19
	v_cvt_pk_bf16_f32 v246, v12, v13
	v_cvt_pk_bf16_f32 v247, v14, v15
	global_store_dwordx4 v201, v[244:247], s[44:45]
	v_pk_add_f32 v[8:9], v[8:9], v[152:153]
	v_pk_add_f32 v[10:11], v[10:11], v[154:155]
	v_pk_add_f32 v[4:5], v[4:5], v[156:157]
	v_pk_add_f32 v[6:7], v[6:7], v[158:159]
	v_mul_f32_e32 v8, 0xbfb8aa3b, v8
	v_mul_f32_e32 v9, 0xbfb8aa3b, v9
	v_mul_f32_e32 v10, 0xbfb8aa3b, v10
	v_mul_f32_e32 v11, 0xbfb8aa3b, v11
	v_mul_f32_e32 v4, 0xbfb8aa3b, v4
	v_mul_f32_e32 v5, 0xbfb8aa3b, v5
	v_mul_f32_e32 v6, 0xbfb8aa3b, v6
	v_mul_f32_e32 v7, 0xbfb8aa3b, v7
	v_exp_f32_e32 v8, v8
	v_exp_f32_e32 v9, v9
	v_exp_f32_e32 v10, v10
	v_exp_f32_e32 v11, v11
	v_exp_f32_e32 v4, v4
	v_exp_f32_e32 v5, v5
	v_exp_f32_e32 v6, v6
	v_exp_f32_e32 v7, v7
	v_add_f32_e32 v8, 1.0, v8
	v_add_f32_e32 v9, 1.0, v9
	v_add_f32_e32 v10, 1.0, v10
	v_add_f32_e32 v11, 1.0, v11
	v_add_f32_e32 v4, 1.0, v4
	v_add_f32_e32 v5, 1.0, v5
	v_add_f32_e32 v6, 1.0, v6
	v_add_f32_e32 v7, 1.0, v7
	v_rcp_f32_e32 v8, v8
	v_rcp_f32_e32 v9, v9
	v_rcp_f32_e32 v10, v10
	v_rcp_f32_e32 v11, v11
	v_rcp_f32_e32 v4, v4
	v_rcp_f32_e32 v5, v5
	v_rcp_f32_e32 v6, v6
	v_rcp_f32_e32 v7, v7
	s_cmp_gt_u32 s42, 1
	s_cbranch_scc1 .Llo_ns15
	v_mul_f32_e32 v8, 0x3f1b4598, v8
	v_mul_f32_e32 v9, 0x3f1b4598, v9
	v_mul_f32_e32 v10, 0x3f1b4598, v10
	v_mul_f32_e32 v11, 0x3f1b4598, v11
	v_mul_f32_e32 v4, 0x3f1b4598, v4
	v_mul_f32_e32 v5, 0x3f1b4598, v5
	v_mul_f32_e32 v6, 0x3f1b4598, v6
	v_mul_f32_e32 v7, 0x3f1b4598, v7
.Llo_ns15:
	s_nop 0
	v_cvt_pk_bf16_f32 v248, v8, v9
	v_cvt_pk_bf16_f32 v249, v10, v11
	v_cvt_pk_bf16_f32 v250, v4, v5
	v_cvt_pk_bf16_f32 v251, v6, v7
	global_store_dwordx4 v201, v[248:251], s[44:45] offset:256
	s_branch .LBB0_1375
.Llo_raw:
	v_cvt_pk_bf16_f32 v244, v128, v129
	v_cvt_pk_bf16_f32 v245, v130, v131
	v_cvt_pk_bf16_f32 v246, v124, v125
	v_cvt_pk_bf16_f32 v247, v126, v127
	global_store_dwordx4 v182, v[244:247], s[44:45]
	v_cvt_pk_bf16_f32 v248, v120, v121
	v_cvt_pk_bf16_f32 v249, v122, v123
	v_cvt_pk_bf16_f32 v250, v116, v117
	v_cvt_pk_bf16_f32 v251, v118, v119
	global_store_dwordx4 v182, v[248:251], s[44:45] offset:256
	v_cvt_pk_bf16_f32 v244, v112, v113
	v_cvt_pk_bf16_f32 v245, v114, v115
	v_cvt_pk_bf16_f32 v246, v108, v109
	v_cvt_pk_bf16_f32 v247, v110, v111
	global_store_dwordx4 v183, v[244:247], s[44:45]
	v_cvt_pk_bf16_f32 v248, v104, v105
	v_cvt_pk_bf16_f32 v249, v106, v107
	v_cvt_pk_bf16_f32 v250, v100, v101
	v_cvt_pk_bf16_f32 v251, v102, v103
	global_store_dwordx4 v183, v[248:251], s[44:45] offset:256
	v_cvt_pk_bf16_f32 v244, v96, v97
	v_cvt_pk_bf16_f32 v245, v98, v99
	v_cvt_pk_bf16_f32 v246, v92, v93
	v_cvt_pk_bf16_f32 v247, v94, v95
	global_store_dwordx4 v184, v[244:247], s[44:45]
	v_cvt_pk_bf16_f32 v248, v88, v89
	v_cvt_pk_bf16_f32 v249, v90, v91
	v_cvt_pk_bf16_f32 v250, v84, v85
	v_cvt_pk_bf16_f32 v251, v86, v87
	global_store_dwordx4 v184, v[248:251], s[44:45] offset:256
	v_cvt_pk_bf16_f32 v244, v80, v81
	v_cvt_pk_bf16_f32 v245, v82, v83
	v_cvt_pk_bf16_f32 v246, v76, v77
	v_cvt_pk_bf16_f32 v247, v78, v79
	global_store_dwordx4 v185, v[244:247], s[44:45]
	v_cvt_pk_bf16_f32 v248, v72, v73
	v_cvt_pk_bf16_f32 v249, v74, v75
	v_cvt_pk_bf16_f32 v250, v68, v69
	v_cvt_pk_bf16_f32 v251, v70, v71
	global_store_dwordx4 v185, v[248:251], s[44:45] offset:256
	v_cvt_pk_bf16_f32 v244, v64, v65
	v_cvt_pk_bf16_f32 v245, v66, v67
	v_cvt_pk_bf16_f32 v246, v60, v61
	v_cvt_pk_bf16_f32 v247, v62, v63
	global_store_dwordx4 v190, v[244:247], s[44:45]
	v_cvt_pk_bf16_f32 v248, v56, v57
	v_cvt_pk_bf16_f32 v249, v58, v59
	v_cvt_pk_bf16_f32 v250, v52, v53
	v_cvt_pk_bf16_f32 v251, v54, v55
	global_store_dwordx4 v190, v[248:251], s[44:45] offset:256
	v_cvt_pk_bf16_f32 v244, v48, v49
	v_cvt_pk_bf16_f32 v245, v50, v51
	v_cvt_pk_bf16_f32 v246, v44, v45
	v_cvt_pk_bf16_f32 v247, v46, v47
	global_store_dwordx4 v191, v[244:247], s[44:45]
	v_cvt_pk_bf16_f32 v248, v40, v41
	v_cvt_pk_bf16_f32 v249, v42, v43
	v_cvt_pk_bf16_f32 v250, v36, v37
	v_cvt_pk_bf16_f32 v251, v38, v39
	global_store_dwordx4 v191, v[248:251], s[44:45] offset:256
	v_cvt_pk_bf16_f32 v244, v32, v33
	v_cvt_pk_bf16_f32 v245, v34, v35
	v_cvt_pk_bf16_f32 v246, v28, v29
	v_cvt_pk_bf16_f32 v247, v30, v31
	global_store_dwordx4 v200, v[244:247], s[44:45]
	v_cvt_pk_bf16_f32 v248, v24, v25
	v_cvt_pk_bf16_f32 v249, v26, v27
	v_cvt_pk_bf16_f32 v250, v20, v21
	v_cvt_pk_bf16_f32 v251, v22, v23
	global_store_dwordx4 v200, v[248:251], s[44:45] offset:256
	v_cvt_pk_bf16_f32 v244, v16, v17
	v_cvt_pk_bf16_f32 v245, v18, v19
	v_cvt_pk_bf16_f32 v246, v12, v13
	v_cvt_pk_bf16_f32 v247, v14, v15
	global_store_dwordx4 v201, v[244:247], s[44:45]
	v_cvt_pk_bf16_f32 v248, v8, v9
	v_cvt_pk_bf16_f32 v249, v10, v11
	v_cvt_pk_bf16_f32 v250, v4, v5
	v_cvt_pk_bf16_f32 v251, v6, v7
	global_store_dwordx4 v201, v[248:251], s[44:45] offset:256
	s_branch .LBB0_1375
